# v48: v41 with barrier waiter poll interval s_sleep 12
# baseline (speedup 1.0000x reference)
.Lxb0_wait:
	global_load_dword v248, v253, s[60:61] sc1
	v_add_u32_e32 v252, 1, v252
	s_waitcnt vmcnt(0)
	v_cmp_ge_u32_e32 vcc, v248, v249
	s_cbranch_vccnz .Lxb0_wdone
	v_cmp_gt_u32_e32 vcc, 0x100000, v252
	s_cbranch_vccz .Lxb0_wdone
	s_sleep 12
	s_branch .Lxb0_wait
